# phase-3 attention: q block loaded with coalesced dwordx4 loads and transposed through wave-private LDS in the prologue (on top of v38)
# speedup vs baseline: 1.0104x; 1.0003x over previous
.Lat3_m5skip:
	s_or_b64 exec, exec, s[16:17]
	v_and_b32_e32 v10, 0xffffffc0, v2
	v_and_b32_e32 v16, 31, v2
	v_bfe_u32 v17, v2, 5, 1
	v_add_u32_e32 v2, 1, v18
	v_cndmask_b32_e64 v111, v2, 33, s[14:15]
	v_or_b32_e32 v2, v19, v16
	v_ashrrev_i32_e32 v3, 31, v2
	v_lshl_add_u32 v126, v0, 8, v10
	v_lshlrev_b64 v[8:9], 10, v[2:3]
	v_ashrrev_i32_e32 v127, 31, v126
	v_lshlrev_b64 v[2:3], 11, v[2:3]
	v_lshl_add_u64 v[8:9], s[8:9], 0, v[8:9]
	v_lshlrev_b64 v[10:11], 1, v[126:127]
	v_lshl_add_u64 v[130:131], s[88:89], 0, v[2:3]
	v_lshl_add_u64 v[8:9], v[8:9], 0, v[10:11]
	v_lshlrev_b32_e32 v0, 3, v17
	v_lshlrev_b32_e32 v132, 4, v17
	v_mov_b32_e32 v133, v1
	v_lshl_add_u64 v[2:3], v[130:131], 0, v[10:11]
	v_lshl_add_u64 v[8:9], v[8:9], 0, v[132:133]
	v_lshl_add_u64 v[2:3], v[2:3], 0, v[0:1]
	s_mov_b64 s[16:17], 0x12e80400
	v_and_b32_e32 v216, 31, v198
	v_lshrrev_b32_e32 v217, 5, v198
	v_lshrrev_b32_e32 v218, 3, v198
	v_and_b32_e32 v219, 7, v198
	v_sub_u32_e32 v220, v218, v216
	v_lshlrev_b32_e32 v220, 10, v220
	v_lshl_add_u32 v220, v219, 4, v220
	v_lshlrev_b32_e32 v217, 4, v217
	v_sub_u32_e32 v220, v220, v217
	v_ashrrev_i32_e32 v221, 31, v220
	v_lshl_add_u64 v[222:223], v[8:9], 0, v[220:221]
	v_mov_b32_e32 v220, 0x2000
	v_mov_b32_e32 v221, 0
	global_load_dwordx4 v[80:83], v[222:223], off
	v_lshl_add_u64 v[222:223], v[222:223], 0, v[220:221]
	global_load_dwordx4 v[84:87], v[222:223], off
	v_lshl_add_u64 v[222:223], v[222:223], 0, v[220:221]
	global_load_dwordx4 v[88:91], v[222:223], off
	v_lshl_add_u64 v[222:223], v[222:223], 0, v[220:221]
	global_load_dwordx4 v[92:95], v[222:223], off
	v_lshl_add_u64 v[8:9], v[2:3], 0, s[16:17]
	s_mov_b32 s16, 0x12e80000
	v_add_co_u32_e32 v2, vcc, s16, v2
	v_mov_b32_e32 v109, v1
	s_nop 0
	v_addc_co_u32_e32 v3, vcc, 0, v3, vcc
	v_and_b32_e32 v216, 31, v198
	v_lshrrev_b32_e32 v217, 5, v198
	v_lshlrev_b32_e32 v217, 3, v217
	v_lshrrev_b32_e32 v218, 3, v198
	v_and_b32_e32 v219, 7, v198
	v_sub_u32_e32 v220, v218, v216
	v_lshlrev_b32_e32 v220, 11, v220
	v_lshl_add_u32 v220, v219, 4, v220
	v_sub_u32_e32 v220, v220, v217
	v_ashrrev_i32_e32 v221, 31, v220
	v_lshl_add_u64 v[222:223], v[8:9], 0, v[220:221]
	v_lshrrev_b32_e32 v218, 4, v198
	v_and_b32_e32 v219, 15, v198
	v_sub_u32_e32 v220, v218, v216
	v_add_u32_e32 v220, 24, v220
	v_lshlrev_b32_e32 v220, 11, v220
	v_lshl_add_u32 v220, v219, 3, v220
	v_sub_u32_e32 v220, v220, v217
	v_ashrrev_i32_e32 v221, 31, v220
	v_lshl_add_u64 v[218:219], v[8:9], 0, v[220:221]
	v_mov_b32_e32 v220, 0x4000
	v_mov_b32_e32 v221, 0
	global_load_dwordx4 v[112:115], v[222:223], off
	v_lshl_add_u64 v[222:223], v[222:223], 0, v[220:221]
	global_load_dwordx4 v[116:119], v[222:223], off
	v_lshl_add_u64 v[222:223], v[222:223], 0, v[220:221]
	global_load_dwordx4 v[120:123], v[222:223], off
	v_mov_b32_e32 v220, 0x2000
	global_load_dwordx2 v[124:125], v[218:219], off
	v_lshl_add_u64 v[218:219], v[218:219], 0, v[220:221]
	global_load_dwordx2 v[128:129], v[218:219], off
	v_lshl_add_u64 v[2:3], v[4:5], 0, v[106:107]
	v_lshl_add_u64 v[2:3], v[2:3], 0, v[108:109]
	v_cndmask_b32_e64 v0, v145, v151, s[14:15]
	v_cmp_lt_u32_e32 vcc, 1, v111
	global_load_dwordx4 v[8:11], v[2:3], off
	v_mad_i64_i32 v[2:3], s[14:15], v0, v104, 0
	v_cndmask_b32_e64 v0, 0, 64, vcc
	v_lshl_add_u64 v[2:3], v[2:3], 1, v[6:7]
	v_add_u32_e32 v6, v0, v104
	v_ashrrev_i32_e32 v7, 31, v6
	v_lshlrev_b64 v[6:7], 7, v[6:7]
	v_add_u32_e32 v133, -1, v111
	v_lshl_add_u64 v[6:7], v[4:5], 0, v[6:7]
	v_min_u32_e32 v18, 2, v133
	v_lshl_add_u64 v[6:7], v[6:7], 0, v[108:109]
	v_lshlrev_b32_e32 v0, 1, v0
	global_load_dwordx4 v[48:51], v[6:7], off
	v_lshl_add_u64 v[6:7], v[2:3], 0, v[0:1]
	v_lshlrev_b32_e32 v0, 7, v18
	v_lshl_add_u64 v[134:135], v[2:3], 0, v[108:109]
	v_lshl_add_u64 v[2:3], v[2:3], 0, v[0:1]
	v_lshl_add_u64 v[6:7], v[6:7], 0, v[108:109]
	v_lshl_add_u64 v[2:3], v[2:3], 0, v[108:109]
	global_load_dwordx4 v[52:55], v[6:7], off
	global_load_dwordx4 v[100:103], v[2:3], off
	v_lshl_add_u32 v6, v18, 6, v104
	v_ashrrev_i32_e32 v7, 31, v6
	v_lshlrev_b64 v[6:7], 7, v[6:7]
	global_load_dwordx4 v[12:15], v[134:135], off
	v_lshl_add_u64 v[6:7], v[4:5], 0, v[6:7]
	v_lshl_add_u64 v[6:7], v[6:7], 0, v[108:109]
	global_load_dwordx4 v[96:99], v[6:7], off
	s_waitcnt vmcnt(15)
	s_movk_i32 s16, 0x420
	v_cmp_gt_i32_e32 vcc, s16, v211
	s_and_saveexec_b64 s[16:17], vcc
	ds_write_b64 v210, v[208:209]
	s_or_b64 exec, exec, s[16:17]
	s_movk_i32 s16, 0x320
	v_cmp_gt_i32_e32 vcc, s16, v211
	s_and_saveexec_b64 s[16:17], vcc
	ds_write_b64 v210, v[200:201] offset:2048
	s_or_b64 exec, exec, s[16:17]
	s_movk_i32 s16, 0x220
	v_cmp_gt_i32_e32 vcc, s16, v211
	s_and_saveexec_b64 s[16:17], vcc
	ds_write_b64 v210, v[202:203] offset:4096
	s_or_b64 exec, exec, s[16:17]
	s_movk_i32 s16, 0x120
	v_cmp_gt_i32_e32 vcc, s16, v211
	s_and_saveexec_b64 s[16:17], vcc
	ds_write_b64 v210, v[204:205] offset:6144
	s_or_b64 exec, exec, s[16:17]
	v_cmp_gt_i32_e32 vcc, 32, v211
	s_and_saveexec_b64 s[16:17], vcc
	ds_write_b64 v210, v[206:207] offset:8192
	s_or_b64 exec, exec, s[16:17]
	v_mov_b32_e32 v2, v1
	v_mov_b32_e32 v3, v1
	v_lshlrev_b32_e32 v136, 2, v17
	v_lshl_add_u64 v[138:139], v[4:5], 0, v[108:109]
	v_mul_u32_u24_e32 v109, 0x90, v16
	v_mad_u32_u24 v152, v16, s43, v141
	v_mov_b32_e32 v0, v1
	v_mov_b32_e32 v4, v1
	v_mov_b32_e32 v5, v1
	v_mov_b32_e32 v6, v1
	v_mov_b32_e32 v7, v1
	s_mov_b32 s19, 0
	v_mov_b32_e32 v154, 0xf149f2ca
	v_mov_b32_e32 v153, 0
	s_mov_b64 s[14:15], 0
	s_waitcnt vmcnt(5)
	ds_write_b128 v105, v[8:11]
	s_waitcnt vmcnt(1)
	ds_write_b128 v143, v[12:15]
	v_lshrrev_b32_e32 v216, 6, v140
	v_mul_u32_u24_e32 v216, 0x1200, v216
	v_add_u32_e32 v216, v216, v141
	v_add_u32_e32 v216, 0x3000, v216
	v_and_b32_e32 v218, 31, v198
	v_lshrrev_b32_e32 v219, 5, v198
	v_mul_u32_u24_e32 v217, 0x90, v218
	v_lshl_add_u32 v217, v219, 4, v217
	v_add_u32_e32 v217, v217, v216
	v_lshrrev_b32_e32 v218, 3, v198
	v_and_b32_e32 v219, 7, v198
	v_mul_u32_u24_e32 v218, 0x90, v218
	v_lshl_add_u32 v218, v219, 4, v218
	v_add_u32_e32 v216, v218, v216
	ds_write_b128 v216, v[80:83]
	ds_write_b128 v216, v[84:87] offset:1152
	ds_write_b128 v216, v[88:91] offset:2304
	ds_write_b128 v216, v[92:95] offset:3456
	s_waitcnt lgkmcnt(0)
	ds_read_b128 v[80:83], v217
	ds_read_b128 v[84:87], v217 offset:32
	ds_read_b128 v[88:91], v217 offset:64
	ds_read_b128 v[92:95], v217 offset:96
	v_mov_b32_e32 v14, v1
	v_mov_b32_e32 v15, v1
	v_mov_b32_e32 v8, v1
	v_mov_b32_e32 v9, v1
	v_mov_b32_e32 v10, v1
	v_mov_b32_e32 v11, v1
	v_mov_b32_e32 v12, v1
	v_mov_b32_e32 v13, v1
	v_mov_b64_e32 v[30:31], v[14:15]
	v_mov_b64_e32 v[46:47], v[14:15]
	v_mov_b64_e32 v[28:29], v[12:13]
	v_mov_b64_e32 v[26:27], v[10:11]
	v_mov_b64_e32 v[24:25], v[8:9]
	v_mov_b64_e32 v[22:23], v[6:7]
	v_mov_b64_e32 v[20:21], v[4:5]
	v_mov_b64_e32 v[18:19], v[2:3]
	v_mov_b64_e32 v[16:17], v[0:1]
	v_mov_b64_e32 v[44:45], v[12:13]
	v_mov_b64_e32 v[42:43], v[10:11]
	v_mov_b64_e32 v[40:41], v[8:9]
	v_mov_b64_e32 v[38:39], v[6:7]
	v_mov_b64_e32 v[36:37], v[4:5]
	v_mov_b64_e32 v[34:35], v[2:3]
	v_mov_b64_e32 v[32:33], v[0:1]
	s_waitcnt lgkmcnt(0)
	s_barrier
	s_branch .LBB0_803
